# sigmoid gate tiles stored tile-compact inside the gate columns (1 KiB contiguous wave stores in P1, same order read back in the P3 merge epilogue)
# speedup vs baseline: 1.0262x; 1.0014x over previous
.LBB0_134:
	s_lshl_b32 s88, s26, 8
	s_lshl_b32 s89, s48, 3
	s_add_i32 s88, s88, s89
	s_mul_i32 s88, s88, 0xc000
	s_add_u32 s86, s74, s88
	s_addc_u32 s87, s75, 0
	s_add_u32 s86, s86, 0x8000
	s_addc_u32 s87, s87, 0
	v_lshlrev_b32_e32 v240, 4, v183
	v_lshl_add_u32 v2, s48, 8, v186
	v_lshl_add_u32 v4, s26, 8, v184
	v_ashrrev_i32_e32 v3, 31, v2
	v_mov_b64_e32 v[0:1], s[74:75]
	v_mad_i64_i32 v[6:7], s[28:29], v4, s47, v[0:1]
	v_lshlrev_b64 v[2:3], 1, v[2:3]
	s_nop 15
	s_nop 15
	v_lshl_add_u64 v[10:11], v[6:7], 0, v[2:3]
	v_pk_mul_f32 v[6:7], v[158:159], s[14:15] op_sel_hi:[1,0]
	v_pk_mul_f32 v[8:9], v[156:157], s[14:15] op_sel_hi:[1,0]
	v_pk_mul_f32 v[12:13], v[152:153], s[14:15] op_sel_hi:[1,0]
	v_pk_mul_f32 v[14:15], v[154:155], s[14:15] op_sel_hi:[1,0]
	v_mul_f32_e32 v6, 0xbfb8aa3b, v6
	v_mul_f32_e32 v5, 0xbfb8aa3b, v8
	v_mul_f32_e32 v8, 0xbfb8aa3b, v12
	v_mul_f32_e32 v12, 0xbfb8aa3b, v13
	v_exp_f32_e32 v6, v6
	v_mul_f32_e32 v13, 0xbfb8aa3b, v14
	v_exp_f32_e32 v13, v13
	v_mul_f32_e32 v7, 0xbfb8aa3b, v7
	v_add_f32_e32 v6, 1.0, v6
	v_mul_f32_e32 v9, 0xbfb8aa3b, v9
	v_rcp_f32_e32 v14, v6
	v_add_f32_e32 v6, 1.0, v13
	v_exp_f32_e32 v7, v7
	v_mul_f32_e32 v13, 0xbfb8aa3b, v15
	v_exp_f32_e32 v5, v5
	v_exp_f32_e32 v8, v8
	v_exp_f32_e32 v9, v9
	v_exp_f32_e32 v12, v12
	v_exp_f32_e32 v13, v13
	v_rcp_f32_e32 v15, v6
	v_add_f32_e32 v6, 1.0, v7
	v_add_f32_e32 v5, 1.0, v5
	v_add_f32_e32 v8, 1.0, v8
	v_add_f32_e32 v9, 1.0, v9
	v_add_f32_e32 v12, 1.0, v12
	v_rcp_f32_e32 v7, v6
	v_add_f32_e32 v6, 1.0, v13
	v_rcp_f32_e32 v5, v5
	v_rcp_f32_e32 v8, v8
	v_rcp_f32_e32 v9, v9
	v_rcp_f32_e32 v12, v12
	v_rcp_f32_e32 v13, v6
	v_cvt_pk_bf16_f32 v7, v14, v7
	v_cvt_pk_bf16_f32 v6, v5, v9
	v_cvt_pk_bf16_f32 v8, v8, v12
	v_cvt_pk_bf16_f32 v9, v15, v13
	global_store_dwordx4 v240, v[6:9], s[86:87]
	v_pk_mul_f32 v[12:13], v[144:145], s[14:15] op_sel_hi:[1,0]
	v_pk_mul_f32 v[14:15], v[146:147], s[14:15] op_sel_hi:[1,0]
	v_pk_mul_f32 v[6:7], v[150:151], s[14:15] op_sel_hi:[1,0]
	v_pk_mul_f32 v[8:9], v[148:149], s[14:15] op_sel_hi:[1,0]
	v_mul_f32_e32 v6, 0xbfb8aa3b, v6
	v_mul_f32_e32 v5, 0xbfb8aa3b, v8
	v_mul_f32_e32 v8, 0xbfb8aa3b, v12
	v_mul_f32_e32 v12, 0xbfb8aa3b, v13
	v_exp_f32_e32 v6, v6
	v_mul_f32_e32 v13, 0xbfb8aa3b, v14
	v_exp_f32_e32 v13, v13
	v_mul_f32_e32 v7, 0xbfb8aa3b, v7
	v_add_f32_e32 v6, 1.0, v6
	v_mul_f32_e32 v9, 0xbfb8aa3b, v9
	v_rcp_f32_e32 v14, v6
	v_add_f32_e32 v6, 1.0, v13
	v_exp_f32_e32 v7, v7
	v_mul_f32_e32 v13, 0xbfb8aa3b, v15
	v_exp_f32_e32 v5, v5
	v_exp_f32_e32 v8, v8
	v_exp_f32_e32 v9, v9
	v_exp_f32_e32 v12, v12
	v_exp_f32_e32 v13, v13
	v_rcp_f32_e32 v15, v6
	v_add_f32_e32 v6, 1.0, v7
	v_add_f32_e32 v5, 1.0, v5
	v_add_f32_e32 v8, 1.0, v8
	v_add_f32_e32 v9, 1.0, v9
	v_add_f32_e32 v12, 1.0, v12
	v_rcp_f32_e32 v7, v6
	v_add_f32_e32 v6, 1.0, v13
	v_rcp_f32_e32 v5, v5
	v_rcp_f32_e32 v8, v8
	v_rcp_f32_e32 v9, v9
	v_rcp_f32_e32 v12, v12
	v_rcp_f32_e32 v13, v6
	v_cvt_pk_bf16_f32 v7, v14, v7
	v_cvt_pk_bf16_f32 v6, v5, v9
	v_cvt_pk_bf16_f32 v8, v8, v12
	v_cvt_pk_bf16_f32 v9, v15, v13
	v_or_b32_e32 v5, 16, v4
	v_add_u32_e32 v241, 0x2000, v240
	global_store_dwordx4 v241, v[6:9], s[86:87]
	v_pk_mul_f32 v[12:13], v[136:137], s[14:15] op_sel_hi:[1,0]
	v_pk_mul_f32 v[14:15], v[138:139], s[14:15] op_sel_hi:[1,0]
	v_mad_i64_i32 v[6:7], s[28:29], v5, s47, v[0:1]
	v_lshl_add_u64 v[10:11], v[6:7], 0, v[2:3]
	v_pk_mul_f32 v[6:7], v[142:143], s[14:15] op_sel_hi:[1,0]
	v_pk_mul_f32 v[8:9], v[140:141], s[14:15] op_sel_hi:[1,0]
	v_mul_f32_e32 v6, 0xbfb8aa3b, v6
	v_mul_f32_e32 v5, 0xbfb8aa3b, v8
	v_mul_f32_e32 v8, 0xbfb8aa3b, v12
	v_mul_f32_e32 v12, 0xbfb8aa3b, v13
	v_exp_f32_e32 v6, v6
	v_mul_f32_e32 v13, 0xbfb8aa3b, v14
	v_exp_f32_e32 v13, v13
	v_mul_f32_e32 v7, 0xbfb8aa3b, v7
	v_add_f32_e32 v6, 1.0, v6
	v_mul_f32_e32 v9, 0xbfb8aa3b, v9
	v_rcp_f32_e32 v14, v6
	v_add_f32_e32 v6, 1.0, v13
	v_exp_f32_e32 v7, v7
	v_mul_f32_e32 v13, 0xbfb8aa3b, v15
	v_exp_f32_e32 v5, v5
	v_exp_f32_e32 v8, v8
	v_exp_f32_e32 v9, v9
	v_exp_f32_e32 v12, v12
	v_exp_f32_e32 v13, v13
	v_rcp_f32_e32 v15, v6
	v_add_f32_e32 v6, 1.0, v7
	v_add_f32_e32 v5, 1.0, v5
	v_add_f32_e32 v8, 1.0, v8
	v_add_f32_e32 v9, 1.0, v9
	v_add_f32_e32 v12, 1.0, v12
	v_rcp_f32_e32 v7, v6
	v_add_f32_e32 v6, 1.0, v13
	v_rcp_f32_e32 v5, v5
	v_rcp_f32_e32 v8, v8
	v_rcp_f32_e32 v9, v9
	v_rcp_f32_e32 v12, v12
	v_rcp_f32_e32 v13, v6
	v_cvt_pk_bf16_f32 v7, v14, v7
	v_cvt_pk_bf16_f32 v6, v5, v9
	v_cvt_pk_bf16_f32 v8, v8, v12
	v_cvt_pk_bf16_f32 v9, v15, v13
	v_add_u32_e32 v241, 0xc000, v240
	global_store_dwordx4 v241, v[6:9], s[86:87]
	v_pk_mul_f32 v[12:13], v[128:129], s[14:15] op_sel_hi:[1,0]
	v_pk_mul_f32 v[14:15], v[130:131], s[14:15] op_sel_hi:[1,0]
	v_pk_mul_f32 v[6:7], v[134:135], s[14:15] op_sel_hi:[1,0]
	v_pk_mul_f32 v[8:9], v[132:133], s[14:15] op_sel_hi:[1,0]
	v_mul_f32_e32 v6, 0xbfb8aa3b, v6
	v_mul_f32_e32 v5, 0xbfb8aa3b, v8
	v_mul_f32_e32 v8, 0xbfb8aa3b, v12
	v_mul_f32_e32 v12, 0xbfb8aa3b, v13
	v_exp_f32_e32 v6, v6
	v_mul_f32_e32 v13, 0xbfb8aa3b, v14
	v_exp_f32_e32 v13, v13
	v_mul_f32_e32 v7, 0xbfb8aa3b, v7
	v_add_f32_e32 v6, 1.0, v6
	v_mul_f32_e32 v9, 0xbfb8aa3b, v9
	v_rcp_f32_e32 v14, v6
	v_add_f32_e32 v6, 1.0, v13
	v_exp_f32_e32 v7, v7
	v_mul_f32_e32 v13, 0xbfb8aa3b, v15
	v_exp_f32_e32 v5, v5
	v_exp_f32_e32 v8, v8
	v_exp_f32_e32 v9, v9
	v_exp_f32_e32 v12, v12
	v_exp_f32_e32 v13, v13
	v_rcp_f32_e32 v15, v6
	v_add_f32_e32 v6, 1.0, v7
	v_add_f32_e32 v5, 1.0, v5
	v_add_f32_e32 v8, 1.0, v8
	v_add_f32_e32 v9, 1.0, v9
	v_add_f32_e32 v12, 1.0, v12
	v_rcp_f32_e32 v7, v6
	v_add_f32_e32 v6, 1.0, v13
	v_rcp_f32_e32 v5, v5
	v_rcp_f32_e32 v8, v8
	v_rcp_f32_e32 v9, v9
	v_rcp_f32_e32 v12, v12
	v_rcp_f32_e32 v13, v6
	v_cvt_pk_bf16_f32 v7, v14, v7
	v_cvt_pk_bf16_f32 v6, v5, v9
	v_cvt_pk_bf16_f32 v8, v8, v12
	v_cvt_pk_bf16_f32 v9, v15, v13
	v_or_b32_e32 v5, 32, v4
	v_add_u32_e32 v241, 0xe000, v240
	global_store_dwordx4 v241, v[6:9], s[86:87]
	v_pk_mul_f32 v[12:13], v[120:121], s[14:15] op_sel_hi:[1,0]
	v_pk_mul_f32 v[14:15], v[122:123], s[14:15] op_sel_hi:[1,0]
	v_mad_i64_i32 v[6:7], s[28:29], v5, s47, v[0:1]
	v_lshl_add_u64 v[10:11], v[6:7], 0, v[2:3]
	v_pk_mul_f32 v[6:7], v[126:127], s[14:15] op_sel_hi:[1,0]
	v_pk_mul_f32 v[8:9], v[124:125], s[14:15] op_sel_hi:[1,0]
	v_mul_f32_e32 v6, 0xbfb8aa3b, v6
	v_mul_f32_e32 v5, 0xbfb8aa3b, v8
	v_mul_f32_e32 v8, 0xbfb8aa3b, v12
	v_mul_f32_e32 v12, 0xbfb8aa3b, v13
	v_exp_f32_e32 v6, v6
	v_mul_f32_e32 v13, 0xbfb8aa3b, v14
	v_exp_f32_e32 v13, v13
	v_mul_f32_e32 v7, 0xbfb8aa3b, v7
	v_add_f32_e32 v6, 1.0, v6
	v_mul_f32_e32 v9, 0xbfb8aa3b, v9
	v_rcp_f32_e32 v14, v6
	v_add_f32_e32 v6, 1.0, v13
	v_exp_f32_e32 v7, v7
	v_mul_f32_e32 v13, 0xbfb8aa3b, v15
	v_exp_f32_e32 v5, v5
	v_exp_f32_e32 v8, v8
	v_exp_f32_e32 v9, v9
	v_exp_f32_e32 v12, v12
	v_exp_f32_e32 v13, v13
	v_rcp_f32_e32 v15, v6
	v_add_f32_e32 v6, 1.0, v7
	v_add_f32_e32 v5, 1.0, v5
	v_add_f32_e32 v8, 1.0, v8
	v_add_f32_e32 v9, 1.0, v9
	v_add_f32_e32 v12, 1.0, v12
	v_rcp_f32_e32 v7, v6
	v_add_f32_e32 v6, 1.0, v13
	v_rcp_f32_e32 v5, v5
	v_rcp_f32_e32 v8, v8
	v_rcp_f32_e32 v9, v9
	v_rcp_f32_e32 v12, v12
	v_rcp_f32_e32 v13, v6
	v_cvt_pk_bf16_f32 v7, v14, v7
	v_cvt_pk_bf16_f32 v6, v5, v9
	v_cvt_pk_bf16_f32 v8, v8, v12
	v_cvt_pk_bf16_f32 v9, v15, v13
	v_add_u32_e32 v241, 0x18000, v240
	global_store_dwordx4 v241, v[6:9], s[86:87]
	v_pk_mul_f32 v[12:13], v[112:113], s[14:15] op_sel_hi:[1,0]
	v_pk_mul_f32 v[14:15], v[114:115], s[14:15] op_sel_hi:[1,0]
	v_pk_mul_f32 v[6:7], v[118:119], s[14:15] op_sel_hi:[1,0]
	v_pk_mul_f32 v[8:9], v[116:117], s[14:15] op_sel_hi:[1,0]
	v_mul_f32_e32 v6, 0xbfb8aa3b, v6
	v_mul_f32_e32 v5, 0xbfb8aa3b, v8
	v_mul_f32_e32 v8, 0xbfb8aa3b, v12
	v_mul_f32_e32 v12, 0xbfb8aa3b, v13
	v_exp_f32_e32 v6, v6
	v_mul_f32_e32 v13, 0xbfb8aa3b, v14
	v_exp_f32_e32 v13, v13
	v_mul_f32_e32 v7, 0xbfb8aa3b, v7
	v_add_f32_e32 v6, 1.0, v6
	v_mul_f32_e32 v9, 0xbfb8aa3b, v9
	v_rcp_f32_e32 v14, v6
	v_add_f32_e32 v6, 1.0, v13
	v_exp_f32_e32 v7, v7
	v_mul_f32_e32 v13, 0xbfb8aa3b, v15
	v_exp_f32_e32 v5, v5
	v_exp_f32_e32 v8, v8
	v_exp_f32_e32 v9, v9
	v_exp_f32_e32 v12, v12
	v_exp_f32_e32 v13, v13
	v_rcp_f32_e32 v15, v6
	v_add_f32_e32 v6, 1.0, v7
	v_add_f32_e32 v5, 1.0, v5
	v_add_f32_e32 v8, 1.0, v8
	v_add_f32_e32 v9, 1.0, v9
	v_add_f32_e32 v12, 1.0, v12
	v_rcp_f32_e32 v7, v6
	v_add_f32_e32 v6, 1.0, v13
	v_rcp_f32_e32 v5, v5
	v_rcp_f32_e32 v8, v8
	v_rcp_f32_e32 v9, v9
	v_rcp_f32_e32 v12, v12
	v_rcp_f32_e32 v13, v6
	v_cvt_pk_bf16_f32 v7, v14, v7
	v_cvt_pk_bf16_f32 v6, v5, v9
	v_cvt_pk_bf16_f32 v8, v8, v12
	v_cvt_pk_bf16_f32 v9, v15, v13
	v_or_b32_e32 v5, 48, v4
	v_add_u32_e32 v241, 0x1a000, v240
	global_store_dwordx4 v241, v[6:9], s[86:87]
	v_pk_mul_f32 v[12:13], v[104:105], s[14:15] op_sel_hi:[1,0]
	v_pk_mul_f32 v[14:15], v[106:107], s[14:15] op_sel_hi:[1,0]
	v_mad_i64_i32 v[6:7], s[28:29], v5, s47, v[0:1]
	v_lshl_add_u64 v[10:11], v[6:7], 0, v[2:3]
	v_pk_mul_f32 v[6:7], v[110:111], s[14:15] op_sel_hi:[1,0]
	v_pk_mul_f32 v[8:9], v[108:109], s[14:15] op_sel_hi:[1,0]
	v_mul_f32_e32 v6, 0xbfb8aa3b, v6
	v_mul_f32_e32 v5, 0xbfb8aa3b, v8
	v_mul_f32_e32 v8, 0xbfb8aa3b, v12
	v_mul_f32_e32 v12, 0xbfb8aa3b, v13
	v_exp_f32_e32 v6, v6
	v_mul_f32_e32 v13, 0xbfb8aa3b, v14
	v_exp_f32_e32 v13, v13
	v_mul_f32_e32 v7, 0xbfb8aa3b, v7
	v_add_f32_e32 v6, 1.0, v6
	v_mul_f32_e32 v9, 0xbfb8aa3b, v9
	v_rcp_f32_e32 v14, v6
	v_add_f32_e32 v6, 1.0, v13
	v_exp_f32_e32 v7, v7
	v_mul_f32_e32 v13, 0xbfb8aa3b, v15
	v_exp_f32_e32 v5, v5
	v_exp_f32_e32 v8, v8
	v_exp_f32_e32 v9, v9
	v_exp_f32_e32 v12, v12
	v_exp_f32_e32 v13, v13
	v_rcp_f32_e32 v15, v6
	v_add_f32_e32 v6, 1.0, v7
	v_add_f32_e32 v5, 1.0, v5
	v_add_f32_e32 v8, 1.0, v8
	v_add_f32_e32 v9, 1.0, v9
	v_add_f32_e32 v12, 1.0, v12
	v_rcp_f32_e32 v7, v6
	v_add_f32_e32 v6, 1.0, v13
	v_rcp_f32_e32 v5, v5
	v_rcp_f32_e32 v8, v8
	v_rcp_f32_e32 v9, v9
	v_rcp_f32_e32 v12, v12
	v_rcp_f32_e32 v13, v6
	v_cvt_pk_bf16_f32 v7, v14, v7
	v_cvt_pk_bf16_f32 v6, v5, v9
	v_cvt_pk_bf16_f32 v8, v8, v12
	v_cvt_pk_bf16_f32 v9, v15, v13
	v_add_u32_e32 v241, 0x24000, v240
	global_store_dwordx4 v241, v[6:9], s[86:87]
	v_pk_mul_f32 v[12:13], v[96:97], s[14:15] op_sel_hi:[1,0]
	v_pk_mul_f32 v[14:15], v[98:99], s[14:15] op_sel_hi:[1,0]
	v_pk_mul_f32 v[6:7], v[102:103], s[14:15] op_sel_hi:[1,0]
	v_pk_mul_f32 v[8:9], v[100:101], s[14:15] op_sel_hi:[1,0]
	v_mul_f32_e32 v6, 0xbfb8aa3b, v6
	v_mul_f32_e32 v5, 0xbfb8aa3b, v8
	v_mul_f32_e32 v8, 0xbfb8aa3b, v12
	v_mul_f32_e32 v12, 0xbfb8aa3b, v13
	v_exp_f32_e32 v6, v6
	v_mul_f32_e32 v13, 0xbfb8aa3b, v14
	v_exp_f32_e32 v13, v13
	v_mul_f32_e32 v7, 0xbfb8aa3b, v7
	v_add_f32_e32 v6, 1.0, v6
	v_mul_f32_e32 v9, 0xbfb8aa3b, v9
	v_rcp_f32_e32 v14, v6
	v_add_f32_e32 v6, 1.0, v13
	v_exp_f32_e32 v7, v7
	v_mul_f32_e32 v13, 0xbfb8aa3b, v15
	v_exp_f32_e32 v5, v5
	v_exp_f32_e32 v8, v8
	v_exp_f32_e32 v9, v9
	v_exp_f32_e32 v12, v12
	v_exp_f32_e32 v13, v13
	v_rcp_f32_e32 v15, v6
	v_add_f32_e32 v6, 1.0, v7
	v_add_f32_e32 v5, 1.0, v5
	v_add_f32_e32 v8, 1.0, v8
	v_add_f32_e32 v9, 1.0, v9
	v_add_f32_e32 v12, 1.0, v12
	v_rcp_f32_e32 v7, v6
	v_add_f32_e32 v6, 1.0, v13
	v_rcp_f32_e32 v5, v5
	v_rcp_f32_e32 v8, v8
	v_rcp_f32_e32 v9, v9
	v_rcp_f32_e32 v12, v12
	v_rcp_f32_e32 v13, v6
	v_cvt_pk_bf16_f32 v7, v14, v7
	v_cvt_pk_bf16_f32 v6, v5, v9
	v_cvt_pk_bf16_f32 v8, v8, v12
	v_cvt_pk_bf16_f32 v9, v15, v13
	v_add_u32_e32 v5, 0x80, v4
	v_add_u32_e32 v241, 0x26000, v240
	global_store_dwordx4 v241, v[6:9], s[86:87]
	v_pk_mul_f32 v[12:13], v[88:89], s[14:15] op_sel_hi:[1,0]
	v_pk_mul_f32 v[14:15], v[90:91], s[14:15] op_sel_hi:[1,0]
	v_mad_i64_i32 v[6:7], s[28:29], v5, s47, v[0:1]
	v_lshl_add_u64 v[10:11], v[6:7], 0, v[2:3]
	v_pk_mul_f32 v[6:7], v[94:95], s[14:15] op_sel_hi:[1,0]
	v_pk_mul_f32 v[8:9], v[92:93], s[14:15] op_sel_hi:[1,0]
	v_mul_f32_e32 v6, 0xbfb8aa3b, v6
	v_mul_f32_e32 v5, 0xbfb8aa3b, v8
	v_mul_f32_e32 v8, 0xbfb8aa3b, v12
	v_mul_f32_e32 v12, 0xbfb8aa3b, v13
	v_exp_f32_e32 v6, v6
	v_mul_f32_e32 v13, 0xbfb8aa3b, v14
	v_exp_f32_e32 v13, v13
	v_mul_f32_e32 v7, 0xbfb8aa3b, v7
	v_add_f32_e32 v6, 1.0, v6
	v_mul_f32_e32 v9, 0xbfb8aa3b, v9
	v_rcp_f32_e32 v14, v6
	v_add_f32_e32 v6, 1.0, v13
	v_exp_f32_e32 v7, v7
	v_mul_f32_e32 v13, 0xbfb8aa3b, v15
	v_exp_f32_e32 v5, v5
	v_exp_f32_e32 v8, v8
	v_exp_f32_e32 v9, v9
	v_exp_f32_e32 v12, v12
	v_exp_f32_e32 v13, v13
	v_rcp_f32_e32 v15, v6
	v_add_f32_e32 v6, 1.0, v7
	v_add_f32_e32 v5, 1.0, v5
	v_add_f32_e32 v8, 1.0, v8
	v_add_f32_e32 v9, 1.0, v9
	v_add_f32_e32 v12, 1.0, v12
	v_rcp_f32_e32 v7, v6
	v_add_f32_e32 v6, 1.0, v13
	v_rcp_f32_e32 v5, v5
	v_rcp_f32_e32 v8, v8
	v_rcp_f32_e32 v9, v9
	v_rcp_f32_e32 v12, v12
	v_rcp_f32_e32 v13, v6
	v_cvt_pk_bf16_f32 v7, v14, v7
	v_cvt_pk_bf16_f32 v6, v5, v9
	v_cvt_pk_bf16_f32 v8, v8, v12
	v_cvt_pk_bf16_f32 v9, v15, v13
	v_add_u32_e32 v241, 0x30000, v240
	global_store_dwordx4 v241, v[6:9], s[86:87]
	v_pk_mul_f32 v[12:13], v[80:81], s[14:15] op_sel_hi:[1,0]
	v_pk_mul_f32 v[14:15], v[82:83], s[14:15] op_sel_hi:[1,0]
	v_pk_mul_f32 v[6:7], v[86:87], s[14:15] op_sel_hi:[1,0]
	v_pk_mul_f32 v[8:9], v[84:85], s[14:15] op_sel_hi:[1,0]
	v_mul_f32_e32 v6, 0xbfb8aa3b, v6
	v_mul_f32_e32 v5, 0xbfb8aa3b, v8
	v_mul_f32_e32 v8, 0xbfb8aa3b, v12
	v_mul_f32_e32 v12, 0xbfb8aa3b, v13
	v_exp_f32_e32 v6, v6
	v_mul_f32_e32 v13, 0xbfb8aa3b, v14
	v_exp_f32_e32 v13, v13
	v_mul_f32_e32 v7, 0xbfb8aa3b, v7
	v_add_f32_e32 v6, 1.0, v6
	v_mul_f32_e32 v9, 0xbfb8aa3b, v9
	v_rcp_f32_e32 v14, v6
	v_add_f32_e32 v6, 1.0, v13
	v_exp_f32_e32 v7, v7
	v_mul_f32_e32 v13, 0xbfb8aa3b, v15
	v_exp_f32_e32 v5, v5
	v_exp_f32_e32 v8, v8
	v_exp_f32_e32 v9, v9
	v_exp_f32_e32 v12, v12
	v_exp_f32_e32 v13, v13
	v_rcp_f32_e32 v15, v6
	v_add_f32_e32 v6, 1.0, v7
	v_add_f32_e32 v5, 1.0, v5
	v_add_f32_e32 v8, 1.0, v8
	v_add_f32_e32 v9, 1.0, v9
	v_add_f32_e32 v12, 1.0, v12
	v_rcp_f32_e32 v7, v6
	v_add_f32_e32 v6, 1.0, v13
	v_rcp_f32_e32 v5, v5
	v_rcp_f32_e32 v8, v8
	v_rcp_f32_e32 v9, v9
	v_rcp_f32_e32 v12, v12
	v_rcp_f32_e32 v13, v6
	v_cvt_pk_bf16_f32 v7, v14, v7
	v_cvt_pk_bf16_f32 v6, v5, v9
	v_cvt_pk_bf16_f32 v8, v8, v12
	v_cvt_pk_bf16_f32 v9, v15, v13
	v_add_u32_e32 v5, 0x90, v4
	v_add_u32_e32 v241, 0x32000, v240
	global_store_dwordx4 v241, v[6:9], s[86:87]
	v_pk_mul_f32 v[12:13], v[72:73], s[14:15] op_sel_hi:[1,0]
	v_pk_mul_f32 v[14:15], v[74:75], s[14:15] op_sel_hi:[1,0]
	v_mad_i64_i32 v[6:7], s[28:29], v5, s47, v[0:1]
	v_lshl_add_u64 v[10:11], v[6:7], 0, v[2:3]
	v_pk_mul_f32 v[6:7], v[78:79], s[14:15] op_sel_hi:[1,0]
	v_pk_mul_f32 v[8:9], v[76:77], s[14:15] op_sel_hi:[1,0]
	v_mul_f32_e32 v6, 0xbfb8aa3b, v6
	v_mul_f32_e32 v5, 0xbfb8aa3b, v8
	v_mul_f32_e32 v8, 0xbfb8aa3b, v12
	v_mul_f32_e32 v12, 0xbfb8aa3b, v13
	v_exp_f32_e32 v6, v6
	v_mul_f32_e32 v13, 0xbfb8aa3b, v14
	v_exp_f32_e32 v13, v13
	v_mul_f32_e32 v7, 0xbfb8aa3b, v7
	v_add_f32_e32 v6, 1.0, v6
	v_mul_f32_e32 v9, 0xbfb8aa3b, v9
	v_rcp_f32_e32 v14, v6
	v_add_f32_e32 v6, 1.0, v13
	v_exp_f32_e32 v7, v7
	v_mul_f32_e32 v13, 0xbfb8aa3b, v15
	v_exp_f32_e32 v5, v5
	v_exp_f32_e32 v8, v8
	v_exp_f32_e32 v9, v9
	v_exp_f32_e32 v12, v12
	v_exp_f32_e32 v13, v13
	v_rcp_f32_e32 v15, v6
	v_add_f32_e32 v6, 1.0, v7
	v_add_f32_e32 v5, 1.0, v5
	v_add_f32_e32 v8, 1.0, v8
	v_add_f32_e32 v9, 1.0, v9
	v_add_f32_e32 v12, 1.0, v12
	v_rcp_f32_e32 v7, v6
	v_add_f32_e32 v6, 1.0, v13
	v_rcp_f32_e32 v5, v5
	v_rcp_f32_e32 v8, v8
	v_rcp_f32_e32 v9, v9
	v_rcp_f32_e32 v12, v12
	v_rcp_f32_e32 v13, v6
	v_cvt_pk_bf16_f32 v7, v14, v7
	v_cvt_pk_bf16_f32 v6, v5, v9
	v_cvt_pk_bf16_f32 v8, v8, v12
	v_cvt_pk_bf16_f32 v9, v15, v13
	v_add_u32_e32 v241, 0x3c000, v240
	global_store_dwordx4 v241, v[6:9], s[86:87]
	v_pk_mul_f32 v[12:13], v[64:65], s[14:15] op_sel_hi:[1,0]
	v_pk_mul_f32 v[14:15], v[66:67], s[14:15] op_sel_hi:[1,0]
	v_pk_mul_f32 v[6:7], v[70:71], s[14:15] op_sel_hi:[1,0]
	v_pk_mul_f32 v[8:9], v[68:69], s[14:15] op_sel_hi:[1,0]
	v_mul_f32_e32 v6, 0xbfb8aa3b, v6
	v_mul_f32_e32 v5, 0xbfb8aa3b, v8
	v_mul_f32_e32 v8, 0xbfb8aa3b, v12
	v_mul_f32_e32 v12, 0xbfb8aa3b, v13
	v_exp_f32_e32 v6, v6
	v_mul_f32_e32 v13, 0xbfb8aa3b, v14
	v_exp_f32_e32 v13, v13
	v_mul_f32_e32 v7, 0xbfb8aa3b, v7
	v_add_f32_e32 v6, 1.0, v6
	v_mul_f32_e32 v9, 0xbfb8aa3b, v9
	v_rcp_f32_e32 v14, v6
	v_add_f32_e32 v6, 1.0, v13
	v_exp_f32_e32 v7, v7
	v_mul_f32_e32 v13, 0xbfb8aa3b, v15
	v_exp_f32_e32 v5, v5
	v_exp_f32_e32 v8, v8
	v_exp_f32_e32 v9, v9
	v_exp_f32_e32 v12, v12
	v_exp_f32_e32 v13, v13
	v_rcp_f32_e32 v15, v6
	v_add_f32_e32 v6, 1.0, v7
	v_add_f32_e32 v5, 1.0, v5
	v_add_f32_e32 v8, 1.0, v8
	v_add_f32_e32 v9, 1.0, v9
	v_add_f32_e32 v12, 1.0, v12
	v_rcp_f32_e32 v7, v6
	v_add_f32_e32 v6, 1.0, v13
	v_rcp_f32_e32 v5, v5
	v_rcp_f32_e32 v8, v8
	v_rcp_f32_e32 v9, v9
	v_rcp_f32_e32 v12, v12
	v_rcp_f32_e32 v13, v6
	v_cvt_pk_bf16_f32 v7, v14, v7
	v_cvt_pk_bf16_f32 v6, v5, v9
	v_cvt_pk_bf16_f32 v8, v8, v12
	v_cvt_pk_bf16_f32 v9, v15, v13
	v_add_u32_e32 v5, 0xa0, v4
	v_add_u32_e32 v241, 0x3e000, v240
	global_store_dwordx4 v241, v[6:9], s[86:87]
	v_pk_mul_f32 v[12:13], v[56:57], s[14:15] op_sel_hi:[1,0]
	v_pk_mul_f32 v[14:15], v[58:59], s[14:15] op_sel_hi:[1,0]
	v_mad_i64_i32 v[6:7], s[28:29], v5, s47, v[0:1]
	v_lshl_add_u64 v[10:11], v[6:7], 0, v[2:3]
	v_pk_mul_f32 v[6:7], v[62:63], s[14:15] op_sel_hi:[1,0]
	v_pk_mul_f32 v[8:9], v[60:61], s[14:15] op_sel_hi:[1,0]
	v_mul_f32_e32 v6, 0xbfb8aa3b, v6
	v_mul_f32_e32 v5, 0xbfb8aa3b, v8
	v_mul_f32_e32 v8, 0xbfb8aa3b, v12
	v_mul_f32_e32 v12, 0xbfb8aa3b, v13
	v_exp_f32_e32 v6, v6
	v_mul_f32_e32 v13, 0xbfb8aa3b, v14
	v_exp_f32_e32 v13, v13
	v_mul_f32_e32 v7, 0xbfb8aa3b, v7
	v_add_f32_e32 v6, 1.0, v6
	v_mul_f32_e32 v9, 0xbfb8aa3b, v9
	v_rcp_f32_e32 v14, v6
	v_add_f32_e32 v6, 1.0, v13
	v_exp_f32_e32 v7, v7
	v_mul_f32_e32 v13, 0xbfb8aa3b, v15
	v_exp_f32_e32 v5, v5
	v_exp_f32_e32 v8, v8
	v_exp_f32_e32 v9, v9
	v_exp_f32_e32 v12, v12
	v_exp_f32_e32 v13, v13
	v_rcp_f32_e32 v15, v6
	v_add_f32_e32 v6, 1.0, v7
	v_add_f32_e32 v5, 1.0, v5
	v_add_f32_e32 v8, 1.0, v8
	v_add_f32_e32 v9, 1.0, v9
	v_add_f32_e32 v12, 1.0, v12
	v_rcp_f32_e32 v7, v6
	v_add_f32_e32 v6, 1.0, v13
	v_rcp_f32_e32 v5, v5
	v_rcp_f32_e32 v8, v8
	v_rcp_f32_e32 v9, v9
	v_rcp_f32_e32 v12, v12
	v_rcp_f32_e32 v13, v6
	v_cvt_pk_bf16_f32 v7, v14, v7
	v_cvt_pk_bf16_f32 v6, v5, v9
	v_cvt_pk_bf16_f32 v8, v8, v12
	v_cvt_pk_bf16_f32 v9, v15, v13
	v_add_u32_e32 v241, 0x48000, v240
	global_store_dwordx4 v241, v[6:9], s[86:87]
	v_pk_mul_f32 v[12:13], v[48:49], s[14:15] op_sel_hi:[1,0]
	v_pk_mul_f32 v[14:15], v[50:51], s[14:15] op_sel_hi:[1,0]
	v_pk_mul_f32 v[6:7], v[54:55], s[14:15] op_sel_hi:[1,0]
	v_pk_mul_f32 v[8:9], v[52:53], s[14:15] op_sel_hi:[1,0]
	v_mul_f32_e32 v6, 0xbfb8aa3b, v6
	v_mul_f32_e32 v5, 0xbfb8aa3b, v8
	v_mul_f32_e32 v8, 0xbfb8aa3b, v12
	v_mul_f32_e32 v12, 0xbfb8aa3b, v13
	v_exp_f32_e32 v6, v6
	v_mul_f32_e32 v13, 0xbfb8aa3b, v14
	v_exp_f32_e32 v13, v13
	v_mul_f32_e32 v7, 0xbfb8aa3b, v7
	v_add_f32_e32 v6, 1.0, v6
	v_mul_f32_e32 v9, 0xbfb8aa3b, v9
	v_rcp_f32_e32 v14, v6
	v_add_f32_e32 v6, 1.0, v13
	v_exp_f32_e32 v7, v7
	v_mul_f32_e32 v13, 0xbfb8aa3b, v15
	v_exp_f32_e32 v5, v5
	v_exp_f32_e32 v8, v8
	v_exp_f32_e32 v9, v9
	v_exp_f32_e32 v12, v12
	v_exp_f32_e32 v13, v13
	v_rcp_f32_e32 v15, v6
	v_add_f32_e32 v6, 1.0, v7
	v_add_f32_e32 v5, 1.0, v5
	v_add_f32_e32 v8, 1.0, v8
	v_add_f32_e32 v9, 1.0, v9
	v_add_f32_e32 v12, 1.0, v12
	v_rcp_f32_e32 v7, v6
	v_add_f32_e32 v6, 1.0, v13
	v_rcp_f32_e32 v5, v5
	v_rcp_f32_e32 v8, v8
	v_rcp_f32_e32 v9, v9
	v_rcp_f32_e32 v12, v12
	v_rcp_f32_e32 v13, v6
	v_add_u32_e32 v4, 0xb0, v4
	v_mad_i64_i32 v[0:1], s[28:29], v4, s47, v[0:1]
	v_cvt_pk_bf16_f32 v6, v5, v9
	v_cvt_pk_bf16_f32 v7, v14, v7
	v_cvt_pk_bf16_f32 v8, v8, v12
	v_cvt_pk_bf16_f32 v9, v15, v13
	v_lshl_add_u64 v[4:5], v[0:1], 0, v[2:3]
	v_pk_mul_f32 v[0:1], v[46:47], s[14:15] op_sel_hi:[1,0]
	v_add_u32_e32 v241, 0x4a000, v240
	global_store_dwordx4 v241, v[6:9], s[86:87]
	v_mul_f32_e32 v0, 0xbfb8aa3b, v0
	v_exp_f32_e32 v0, v0
	v_pk_mul_f32 v[8:9], v[42:43], s[14:15] op_sel_hi:[1,0]
	v_pk_mul_f32 v[2:3], v[44:45], s[14:15] op_sel_hi:[1,0]
	v_mul_f32_e32 v8, 0xbfb8aa3b, v8
	v_exp_f32_e32 v8, v8
	v_pk_mul_f32 v[6:7], v[40:41], s[14:15] op_sel_hi:[1,0]
	v_add_f32_e32 v0, 1.0, v0
	v_mul_f32_e32 v1, 0xbfb8aa3b, v1
	v_mul_f32_e32 v2, 0xbfb8aa3b, v2
	v_mul_f32_e32 v6, 0xbfb8aa3b, v6
	v_mul_f32_e32 v3, 0xbfb8aa3b, v3
	v_mul_f32_e32 v7, 0xbfb8aa3b, v7
	v_rcp_f32_e32 v10, v0
	v_add_f32_e32 v0, 1.0, v8
	v_exp_f32_e32 v1, v1
	v_mul_f32_e32 v8, 0xbfb8aa3b, v9
	v_exp_f32_e32 v2, v2
	v_exp_f32_e32 v6, v6
	v_exp_f32_e32 v3, v3
	v_exp_f32_e32 v7, v7
	v_exp_f32_e32 v8, v8
	v_rcp_f32_e32 v9, v0
	v_add_f32_e32 v0, 1.0, v1
	v_add_f32_e32 v2, 1.0, v2
	v_add_f32_e32 v6, 1.0, v6
	v_add_f32_e32 v3, 1.0, v3
	v_add_f32_e32 v7, 1.0, v7
	v_rcp_f32_e32 v1, v0
	v_add_f32_e32 v0, 1.0, v8
	v_rcp_f32_e32 v2, v2
	v_rcp_f32_e32 v6, v6
	v_rcp_f32_e32 v3, v3
	v_rcp_f32_e32 v7, v7
	v_rcp_f32_e32 v8, v0
	v_cvt_pk_bf16_f32 v1, v10, v1
	v_cvt_pk_bf16_f32 v0, v2, v3
	v_cvt_pk_bf16_f32 v2, v6, v7
	v_cvt_pk_bf16_f32 v3, v9, v8
	v_add_u32_e32 v241, 0x54000, v240
	global_store_dwordx4 v241, v[0:3], s[86:87]
	v_pk_mul_f32 v[8:9], v[34:35], s[14:15] op_sel_hi:[1,0]
	v_pk_mul_f32 v[6:7], v[32:33], s[14:15] op_sel_hi:[1,0]
	v_pk_mul_f32 v[0:1], v[38:39], s[14:15] op_sel_hi:[1,0]
	v_mul_f32_e32 v8, 0xbfb8aa3b, v8
	v_mul_f32_e32 v0, 0xbfb8aa3b, v0
	v_exp_f32_e32 v0, v0
	v_exp_f32_e32 v8, v8
	v_pk_mul_f32 v[2:3], v[36:37], s[14:15] op_sel_hi:[1,0]
	v_mul_f32_e32 v1, 0xbfb8aa3b, v1
	v_add_f32_e32 v0, 1.0, v0
	v_mul_f32_e32 v2, 0xbfb8aa3b, v2
	v_mul_f32_e32 v6, 0xbfb8aa3b, v6
	v_mul_f32_e32 v3, 0xbfb8aa3b, v3
	v_mul_f32_e32 v7, 0xbfb8aa3b, v7
	v_rcp_f32_e32 v10, v0
	v_add_f32_e32 v0, 1.0, v8
	v_exp_f32_e32 v1, v1
	v_mul_f32_e32 v8, 0xbfb8aa3b, v9
	v_exp_f32_e32 v2, v2
	v_exp_f32_e32 v6, v6
	v_exp_f32_e32 v3, v3
	v_exp_f32_e32 v7, v7
	v_exp_f32_e32 v8, v8
	v_rcp_f32_e32 v9, v0
	v_add_f32_e32 v0, 1.0, v1
	v_add_f32_e32 v2, 1.0, v2
	v_add_f32_e32 v6, 1.0, v6
	v_add_f32_e32 v3, 1.0, v3
	v_add_f32_e32 v7, 1.0, v7
	v_rcp_f32_e32 v1, v0
	v_add_f32_e32 v0, 1.0, v8
	v_rcp_f32_e32 v2, v2
	v_rcp_f32_e32 v6, v6
	v_rcp_f32_e32 v3, v3
	v_rcp_f32_e32 v7, v7
	v_rcp_f32_e32 v8, v0
	v_cvt_pk_bf16_f32 v1, v10, v1
	v_cvt_pk_bf16_f32 v0, v2, v3
	v_cvt_pk_bf16_f32 v2, v6, v7
	v_cvt_pk_bf16_f32 v3, v9, v8
	s_andn2_b64 vcc, exec, s[20:21]
	s_mov_b64 s[20:21], -1
	v_add_u32_e32 v241, 0x56000, v240
	global_store_dwordx4 v241, v[0:3], s[86:87]
	s_cbranch_vccnz .LBB0_122
	s_andn2_b64 vcc, exec, s[8:9]
	s_cbranch_vccnz .LBB0_121
	s_barrier
	s_branch .LBB0_121

.LBB0_340:
	s_lshl_b32 s86, s26, 8
	s_lshl_b32 s87, s28, 3
	s_add_i32 s86, s86, s87
	s_mul_i32 s86, s86, 0xc000
	s_add_u32 s78, s74, s86
	s_addc_u32 s79, s75, 0
	s_add_u32 s78, s78, 0x8000
	s_addc_u32 s79, s79, 0
	s_add_u32 s76, s78, 0x600000
	s_addc_u32 s77, s79, 0
	s_add_u32 s88, s76, 0x2000
	s_addc_u32 s89, s77, 0
	s_add_u32 s90, s78, 0x2000
	s_addc_u32 s91, s79, 0
	s_lshl_b32 s86, s26, 21
	s_lshl_b32 s87, s28, 9
	s_add_u32 s86, s86, s87
	s_add_u32 s72, s4, s86
	s_addc_u32 s73, s5, 0
	v_lshlrev_b32_e32 v142, 4, v183
	v_lshlrev_b32_e32 v143, 13, v162
	v_lshl_add_u32 v143, v164, 1, v143
	s_cmp_eq_u32 s33, 0
	s_cselect_b64 s[0:1], -1, 0
	s_cbranch_scc0 .Lp3e_half1
	global_load_dwordx4 v[166:169], v142, s[76:77]
	global_load_dwordx4 v[170:173], v142, s[78:79]
	global_load_dwordx4 v[174:177], v142, s[88:89]
	global_load_dwordx4 v[178:181], v142, s[90:91]
	v_add_u32_e32 v145, 0xc000, v142
	global_load_dwordx4 v[184:187], v145, s[76:77]
	global_load_dwordx4 v[188:191], v145, s[78:79]
	global_load_dwordx4 v[192:195], v145, s[88:89]
	global_load_dwordx4 v[196:199], v145, s[90:91]
	v_add_u32_e32 v144, 0x18000, v142
	global_load_dwordx4 v[200:203], v144, s[76:77]
	global_load_dwordx4 v[204:207], v144, s[78:79]
	global_load_dwordx4 v[208:211], v144, s[88:89]
	global_load_dwordx4 v[212:215], v144, s[90:91]
	v_add_u32_e32 v145, 0x24000, v142
	global_load_dwordx4 v[216:219], v145, s[76:77]
	global_load_dwordx4 v[220:223], v145, s[78:79]
	global_load_dwordx4 v[224:227], v145, s[88:89]
	global_load_dwordx4 v[228:231], v145, s[90:91]
	s_waitcnt vmcnt(14)
	v_lshlrev_b32_e32 v146, 16, v166
	v_and_b32_e32 v147, 0xffff0000, v166
	v_lshlrev_b32_e32 v148, 16, v167
	v_and_b32_e32 v149, 0xffff0000, v167
	v_lshlrev_b32_e32 v150, 16, v168
	v_and_b32_e32 v151, 0xffff0000, v168
	v_lshlrev_b32_e32 v152, 16, v169
	v_and_b32_e32 v153, 0xffff0000, v169
	v_rcp_f32_e32 v146, v146
	v_rcp_f32_e32 v147, v147
	v_rcp_f32_e32 v148, v148
	v_rcp_f32_e32 v149, v149
	v_rcp_f32_e32 v150, v150
	v_rcp_f32_e32 v151, v151
	v_rcp_f32_e32 v152, v152
	v_rcp_f32_e32 v153, v153
	v_lshlrev_b32_e32 v154, 16, v170
	v_and_b32_e32 v155, 0xffff0000, v170
	v_lshlrev_b32_e32 v156, 16, v171
	v_and_b32_e32 v157, 0xffff0000, v171
	v_lshlrev_b32_e32 v158, 16, v172
	v_and_b32_e32 v159, 0xffff0000, v172
	v_lshlrev_b32_e32 v160, 16, v173
	v_and_b32_e32 v161, 0xffff0000, v173
	v_pk_mul_f32 v[146:147], v[146:147], v[154:155]
	v_pk_mul_f32 v[148:149], v[148:149], v[156:157]
	v_pk_mul_f32 v[150:151], v[150:151], v[158:159]
	v_pk_mul_f32 v[152:153], v[152:153], v[160:161]
	v_pk_mul_f32 v[124:125], v[124:125], v[146:147]
	v_pk_mul_f32 v[126:127], v[126:127], v[148:149]
	v_pk_mul_f32 v[120:121], v[120:121], v[150:151]
	v_pk_mul_f32 v[122:123], v[122:123], v[152:153]
	s_waitcnt vmcnt(12)
	v_lshlrev_b32_e32 v146, 16, v174
	v_and_b32_e32 v147, 0xffff0000, v174
	v_lshlrev_b32_e32 v148, 16, v175
	v_and_b32_e32 v149, 0xffff0000, v175
	v_lshlrev_b32_e32 v150, 16, v176
	v_and_b32_e32 v151, 0xffff0000, v176
	v_lshlrev_b32_e32 v152, 16, v177
	v_and_b32_e32 v153, 0xffff0000, v177
	v_rcp_f32_e32 v146, v146
	v_rcp_f32_e32 v147, v147
	v_rcp_f32_e32 v148, v148
	v_rcp_f32_e32 v149, v149
	v_rcp_f32_e32 v150, v150
	v_rcp_f32_e32 v151, v151
	v_rcp_f32_e32 v152, v152
	v_rcp_f32_e32 v153, v153
	v_lshlrev_b32_e32 v154, 16, v178
	v_and_b32_e32 v155, 0xffff0000, v178
	v_lshlrev_b32_e32 v156, 16, v179
	v_and_b32_e32 v157, 0xffff0000, v179
	v_lshlrev_b32_e32 v158, 16, v180
	v_and_b32_e32 v159, 0xffff0000, v180
	v_lshlrev_b32_e32 v160, 16, v181
	v_and_b32_e32 v161, 0xffff0000, v181
	v_pk_mul_f32 v[146:147], v[146:147], v[154:155]
	v_pk_mul_f32 v[148:149], v[148:149], v[156:157]
	v_pk_mul_f32 v[150:151], v[150:151], v[158:159]
	v_pk_mul_f32 v[152:153], v[152:153], v[160:161]
	v_pk_mul_f32 v[92:93], v[92:93], v[146:147]
	v_pk_mul_f32 v[94:95], v[94:95], v[148:149]
	v_pk_mul_f32 v[88:89], v[88:89], v[150:151]
	v_pk_mul_f32 v[90:91], v[90:91], v[152:153]
	s_waitcnt vmcnt(10)
	v_lshlrev_b32_e32 v146, 16, v184
	v_and_b32_e32 v147, 0xffff0000, v184
	v_lshlrev_b32_e32 v148, 16, v185
	v_and_b32_e32 v149, 0xffff0000, v185
	v_lshlrev_b32_e32 v150, 16, v186
	v_and_b32_e32 v151, 0xffff0000, v186
	v_lshlrev_b32_e32 v152, 16, v187
	v_and_b32_e32 v153, 0xffff0000, v187
	v_rcp_f32_e32 v146, v146
	v_rcp_f32_e32 v147, v147
	v_rcp_f32_e32 v148, v148
	v_rcp_f32_e32 v149, v149
	v_rcp_f32_e32 v150, v150
	v_rcp_f32_e32 v151, v151
	v_rcp_f32_e32 v152, v152
	v_rcp_f32_e32 v153, v153
	v_lshlrev_b32_e32 v154, 16, v188
	v_and_b32_e32 v155, 0xffff0000, v188
	v_lshlrev_b32_e32 v156, 16, v189
	v_and_b32_e32 v157, 0xffff0000, v189
	v_lshlrev_b32_e32 v158, 16, v190
	v_and_b32_e32 v159, 0xffff0000, v190
	v_lshlrev_b32_e32 v160, 16, v191
	v_and_b32_e32 v161, 0xffff0000, v191
	v_pk_mul_f32 v[146:147], v[146:147], v[154:155]
	v_pk_mul_f32 v[148:149], v[148:149], v[156:157]
	v_pk_mul_f32 v[150:151], v[150:151], v[158:159]
	v_pk_mul_f32 v[152:153], v[152:153], v[160:161]
	v_pk_mul_f32 v[116:117], v[116:117], v[146:147]
	v_pk_mul_f32 v[118:119], v[118:119], v[148:149]
	v_pk_mul_f32 v[112:113], v[112:113], v[150:151]
	v_pk_mul_f32 v[114:115], v[114:115], v[152:153]
	s_waitcnt vmcnt(8)
	v_lshlrev_b32_e32 v146, 16, v192
	v_and_b32_e32 v147, 0xffff0000, v192
	v_lshlrev_b32_e32 v148, 16, v193
	v_and_b32_e32 v149, 0xffff0000, v193
	v_lshlrev_b32_e32 v150, 16, v194
	v_and_b32_e32 v151, 0xffff0000, v194
	v_lshlrev_b32_e32 v152, 16, v195
	v_and_b32_e32 v153, 0xffff0000, v195
	v_rcp_f32_e32 v146, v146
	v_rcp_f32_e32 v147, v147
	v_rcp_f32_e32 v148, v148
	v_rcp_f32_e32 v149, v149
	v_rcp_f32_e32 v150, v150
	v_rcp_f32_e32 v151, v151
	v_rcp_f32_e32 v152, v152
	v_rcp_f32_e32 v153, v153
	v_lshlrev_b32_e32 v154, 16, v196
	v_and_b32_e32 v155, 0xffff0000, v196
	v_lshlrev_b32_e32 v156, 16, v197
	v_and_b32_e32 v157, 0xffff0000, v197
	v_lshlrev_b32_e32 v158, 16, v198
	v_and_b32_e32 v159, 0xffff0000, v198
	v_lshlrev_b32_e32 v160, 16, v199
	v_and_b32_e32 v161, 0xffff0000, v199
	v_pk_mul_f32 v[146:147], v[146:147], v[154:155]
	v_pk_mul_f32 v[148:149], v[148:149], v[156:157]
	v_pk_mul_f32 v[150:151], v[150:151], v[158:159]
	v_pk_mul_f32 v[152:153], v[152:153], v[160:161]
	v_pk_mul_f32 v[84:85], v[84:85], v[146:147]
	v_pk_mul_f32 v[86:87], v[86:87], v[148:149]
	v_pk_mul_f32 v[80:81], v[80:81], v[150:151]
	v_pk_mul_f32 v[82:83], v[82:83], v[152:153]
	v_add_u32_e32 v144, 0x30000, v142
	global_load_dwordx4 v[166:169], v144, s[76:77]
	global_load_dwordx4 v[170:173], v144, s[78:79]
	global_load_dwordx4 v[174:177], v144, s[88:89]
	global_load_dwordx4 v[178:181], v144, s[90:91]
	v_add_u32_e32 v145, 0x3c000, v142
	global_load_dwordx4 v[184:187], v145, s[76:77]
	global_load_dwordx4 v[188:191], v145, s[78:79]
	global_load_dwordx4 v[192:195], v145, s[88:89]
	global_load_dwordx4 v[196:199], v145, s[90:91]
	s_waitcnt vmcnt(14)
	v_lshlrev_b32_e32 v146, 16, v200
	v_and_b32_e32 v147, 0xffff0000, v200
	v_lshlrev_b32_e32 v148, 16, v201
	v_and_b32_e32 v149, 0xffff0000, v201
	v_lshlrev_b32_e32 v150, 16, v202
	v_and_b32_e32 v151, 0xffff0000, v202
	v_lshlrev_b32_e32 v152, 16, v203
	v_and_b32_e32 v153, 0xffff0000, v203
	v_rcp_f32_e32 v146, v146
	v_rcp_f32_e32 v147, v147
	v_rcp_f32_e32 v148, v148
	v_rcp_f32_e32 v149, v149
	v_rcp_f32_e32 v150, v150
	v_rcp_f32_e32 v151, v151
	v_rcp_f32_e32 v152, v152
	v_rcp_f32_e32 v153, v153
	v_lshlrev_b32_e32 v154, 16, v204
	v_and_b32_e32 v155, 0xffff0000, v204
	v_lshlrev_b32_e32 v156, 16, v205
	v_and_b32_e32 v157, 0xffff0000, v205
	v_lshlrev_b32_e32 v158, 16, v206
	v_and_b32_e32 v159, 0xffff0000, v206
	v_lshlrev_b32_e32 v160, 16, v207
	v_and_b32_e32 v161, 0xffff0000, v207
	v_pk_mul_f32 v[146:147], v[146:147], v[154:155]
	v_pk_mul_f32 v[148:149], v[148:149], v[156:157]
	v_pk_mul_f32 v[150:151], v[150:151], v[158:159]
	v_pk_mul_f32 v[152:153], v[152:153], v[160:161]
	v_pk_mul_f32 v[108:109], v[108:109], v[146:147]
	v_pk_mul_f32 v[110:111], v[110:111], v[148:149]
	v_pk_mul_f32 v[104:105], v[104:105], v[150:151]
	v_pk_mul_f32 v[106:107], v[106:107], v[152:153]
	s_waitcnt vmcnt(12)
	v_lshlrev_b32_e32 v146, 16, v208
	v_and_b32_e32 v147, 0xffff0000, v208
	v_lshlrev_b32_e32 v148, 16, v209
	v_and_b32_e32 v149, 0xffff0000, v209
	v_lshlrev_b32_e32 v150, 16, v210
	v_and_b32_e32 v151, 0xffff0000, v210
	v_lshlrev_b32_e32 v152, 16, v211
	v_and_b32_e32 v153, 0xffff0000, v211
	v_rcp_f32_e32 v146, v146
	v_rcp_f32_e32 v147, v147
	v_rcp_f32_e32 v148, v148
	v_rcp_f32_e32 v149, v149
	v_rcp_f32_e32 v150, v150
	v_rcp_f32_e32 v151, v151
	v_rcp_f32_e32 v152, v152
	v_rcp_f32_e32 v153, v153
	v_lshlrev_b32_e32 v154, 16, v212
	v_and_b32_e32 v155, 0xffff0000, v212
	v_lshlrev_b32_e32 v156, 16, v213
	v_and_b32_e32 v157, 0xffff0000, v213
	v_lshlrev_b32_e32 v158, 16, v214
	v_and_b32_e32 v159, 0xffff0000, v214
	v_lshlrev_b32_e32 v160, 16, v215
	v_and_b32_e32 v161, 0xffff0000, v215
	v_pk_mul_f32 v[146:147], v[146:147], v[154:155]
	v_pk_mul_f32 v[148:149], v[148:149], v[156:157]
	v_pk_mul_f32 v[150:151], v[150:151], v[158:159]
	v_pk_mul_f32 v[152:153], v[152:153], v[160:161]
	v_pk_mul_f32 v[76:77], v[76:77], v[146:147]
	v_pk_mul_f32 v[78:79], v[78:79], v[148:149]
	v_pk_mul_f32 v[72:73], v[72:73], v[150:151]
	v_pk_mul_f32 v[74:75], v[74:75], v[152:153]
	s_waitcnt vmcnt(10)
	v_lshlrev_b32_e32 v146, 16, v216
	v_and_b32_e32 v147, 0xffff0000, v216
	v_lshlrev_b32_e32 v148, 16, v217
	v_and_b32_e32 v149, 0xffff0000, v217
	v_lshlrev_b32_e32 v150, 16, v218
	v_and_b32_e32 v151, 0xffff0000, v218
	v_lshlrev_b32_e32 v152, 16, v219
	v_and_b32_e32 v153, 0xffff0000, v219
	v_rcp_f32_e32 v146, v146
	v_rcp_f32_e32 v147, v147
	v_rcp_f32_e32 v148, v148
	v_rcp_f32_e32 v149, v149
	v_rcp_f32_e32 v150, v150
	v_rcp_f32_e32 v151, v151
	v_rcp_f32_e32 v152, v152
	v_rcp_f32_e32 v153, v153
	v_lshlrev_b32_e32 v154, 16, v220
	v_and_b32_e32 v155, 0xffff0000, v220
	v_lshlrev_b32_e32 v156, 16, v221
	v_and_b32_e32 v157, 0xffff0000, v221
	v_lshlrev_b32_e32 v158, 16, v222
	v_and_b32_e32 v159, 0xffff0000, v222
	v_lshlrev_b32_e32 v160, 16, v223
	v_and_b32_e32 v161, 0xffff0000, v223
	v_pk_mul_f32 v[146:147], v[146:147], v[154:155]
	v_pk_mul_f32 v[148:149], v[148:149], v[156:157]
	v_pk_mul_f32 v[150:151], v[150:151], v[158:159]
	v_pk_mul_f32 v[152:153], v[152:153], v[160:161]
	v_pk_mul_f32 v[100:101], v[100:101], v[146:147]
	v_pk_mul_f32 v[102:103], v[102:103], v[148:149]
	v_pk_mul_f32 v[96:97], v[96:97], v[150:151]
	v_pk_mul_f32 v[98:99], v[98:99], v[152:153]
	s_waitcnt vmcnt(8)
	v_lshlrev_b32_e32 v146, 16, v224
	v_and_b32_e32 v147, 0xffff0000, v224
	v_lshlrev_b32_e32 v148, 16, v225
	v_and_b32_e32 v149, 0xffff0000, v225
	v_lshlrev_b32_e32 v150, 16, v226
	v_and_b32_e32 v151, 0xffff0000, v226
	v_lshlrev_b32_e32 v152, 16, v227
	v_and_b32_e32 v153, 0xffff0000, v227
	v_rcp_f32_e32 v146, v146
	v_rcp_f32_e32 v147, v147
	v_rcp_f32_e32 v148, v148
	v_rcp_f32_e32 v149, v149
	v_rcp_f32_e32 v150, v150
	v_rcp_f32_e32 v151, v151
	v_rcp_f32_e32 v152, v152
	v_rcp_f32_e32 v153, v153
	v_lshlrev_b32_e32 v154, 16, v228
	v_and_b32_e32 v155, 0xffff0000, v228
	v_lshlrev_b32_e32 v156, 16, v229
	v_and_b32_e32 v157, 0xffff0000, v229
	v_lshlrev_b32_e32 v158, 16, v230
	v_and_b32_e32 v159, 0xffff0000, v230
	v_lshlrev_b32_e32 v160, 16, v231
	v_and_b32_e32 v161, 0xffff0000, v231
	v_pk_mul_f32 v[146:147], v[146:147], v[154:155]
	v_pk_mul_f32 v[148:149], v[148:149], v[156:157]
	v_pk_mul_f32 v[150:151], v[150:151], v[158:159]
	v_pk_mul_f32 v[152:153], v[152:153], v[160:161]
	v_pk_mul_f32 v[68:69], v[68:69], v[146:147]
	v_pk_mul_f32 v[70:71], v[70:71], v[148:149]
	v_pk_mul_f32 v[64:65], v[64:65], v[150:151]
	v_pk_mul_f32 v[66:67], v[66:67], v[152:153]
	v_add_u32_e32 v144, 0x48000, v142
	global_load_dwordx4 v[200:203], v144, s[76:77]
	global_load_dwordx4 v[204:207], v144, s[78:79]
	global_load_dwordx4 v[208:211], v144, s[88:89]
	global_load_dwordx4 v[212:215], v144, s[90:91]
	v_add_u32_e32 v145, 0x54000, v142
	global_load_dwordx4 v[216:219], v145, s[76:77]
	global_load_dwordx4 v[220:223], v145, s[78:79]
	global_load_dwordx4 v[224:227], v145, s[88:89]
	global_load_dwordx4 v[228:231], v145, s[90:91]
	s_waitcnt vmcnt(14)
	v_lshlrev_b32_e32 v146, 16, v166
	v_and_b32_e32 v147, 0xffff0000, v166
	v_lshlrev_b32_e32 v148, 16, v167
	v_and_b32_e32 v149, 0xffff0000, v167
	v_lshlrev_b32_e32 v150, 16, v168
	v_and_b32_e32 v151, 0xffff0000, v168
	v_lshlrev_b32_e32 v152, 16, v169
	v_and_b32_e32 v153, 0xffff0000, v169
	v_rcp_f32_e32 v146, v146
	v_rcp_f32_e32 v147, v147
	v_rcp_f32_e32 v148, v148
	v_rcp_f32_e32 v149, v149
	v_rcp_f32_e32 v150, v150
	v_rcp_f32_e32 v151, v151
	v_rcp_f32_e32 v152, v152
	v_rcp_f32_e32 v153, v153
	v_lshlrev_b32_e32 v154, 16, v170
	v_and_b32_e32 v155, 0xffff0000, v170
	v_lshlrev_b32_e32 v156, 16, v171
	v_and_b32_e32 v157, 0xffff0000, v171
	v_lshlrev_b32_e32 v158, 16, v172
	v_and_b32_e32 v159, 0xffff0000, v172
	v_lshlrev_b32_e32 v160, 16, v173
	v_and_b32_e32 v161, 0xffff0000, v173
	v_pk_mul_f32 v[146:147], v[146:147], v[154:155]
	v_pk_mul_f32 v[148:149], v[148:149], v[156:157]
	v_pk_mul_f32 v[150:151], v[150:151], v[158:159]
	v_pk_mul_f32 v[152:153], v[152:153], v[160:161]
	v_pk_mul_f32 v[60:61], v[60:61], v[146:147]
	v_pk_mul_f32 v[62:63], v[62:63], v[148:149]
	v_pk_mul_f32 v[56:57], v[56:57], v[150:151]
	v_pk_mul_f32 v[58:59], v[58:59], v[152:153]
	s_waitcnt vmcnt(12)
	v_lshlrev_b32_e32 v146, 16, v174
	v_and_b32_e32 v147, 0xffff0000, v174
	v_lshlrev_b32_e32 v148, 16, v175
	v_and_b32_e32 v149, 0xffff0000, v175
	v_lshlrev_b32_e32 v150, 16, v176
	v_and_b32_e32 v151, 0xffff0000, v176
	v_lshlrev_b32_e32 v152, 16, v177
	v_and_b32_e32 v153, 0xffff0000, v177
	v_rcp_f32_e32 v146, v146
	v_rcp_f32_e32 v147, v147
	v_rcp_f32_e32 v148, v148
	v_rcp_f32_e32 v149, v149
	v_rcp_f32_e32 v150, v150
	v_rcp_f32_e32 v151, v151
	v_rcp_f32_e32 v152, v152
	v_rcp_f32_e32 v153, v153
	v_lshlrev_b32_e32 v154, 16, v178
	v_and_b32_e32 v155, 0xffff0000, v178
	v_lshlrev_b32_e32 v156, 16, v179
	v_and_b32_e32 v157, 0xffff0000, v179
	v_lshlrev_b32_e32 v158, 16, v180
	v_and_b32_e32 v159, 0xffff0000, v180
	v_lshlrev_b32_e32 v160, 16, v181
	v_and_b32_e32 v161, 0xffff0000, v181
	v_pk_mul_f32 v[146:147], v[146:147], v[154:155]
	v_pk_mul_f32 v[148:149], v[148:149], v[156:157]
	v_pk_mul_f32 v[150:151], v[150:151], v[158:159]
	v_pk_mul_f32 v[152:153], v[152:153], v[160:161]
	v_pk_mul_f32 v[28:29], v[28:29], v[146:147]
	v_pk_mul_f32 v[30:31], v[30:31], v[148:149]
	v_pk_mul_f32 v[24:25], v[24:25], v[150:151]
	v_pk_mul_f32 v[26:27], v[26:27], v[152:153]
	s_waitcnt vmcnt(10)
	v_lshlrev_b32_e32 v146, 16, v184
	v_and_b32_e32 v147, 0xffff0000, v184
	v_lshlrev_b32_e32 v148, 16, v185
	v_and_b32_e32 v149, 0xffff0000, v185
	v_lshlrev_b32_e32 v150, 16, v186
	v_and_b32_e32 v151, 0xffff0000, v186
	v_lshlrev_b32_e32 v152, 16, v187
	v_and_b32_e32 v153, 0xffff0000, v187
	v_rcp_f32_e32 v146, v146
	v_rcp_f32_e32 v147, v147
	v_rcp_f32_e32 v148, v148
	v_rcp_f32_e32 v149, v149
	v_rcp_f32_e32 v150, v150
	v_rcp_f32_e32 v151, v151
	v_rcp_f32_e32 v152, v152
	v_rcp_f32_e32 v153, v153
	v_lshlrev_b32_e32 v154, 16, v188
	v_and_b32_e32 v155, 0xffff0000, v188
	v_lshlrev_b32_e32 v156, 16, v189
	v_and_b32_e32 v157, 0xffff0000, v189
	v_lshlrev_b32_e32 v158, 16, v190
	v_and_b32_e32 v159, 0xffff0000, v190
	v_lshlrev_b32_e32 v160, 16, v191
	v_and_b32_e32 v161, 0xffff0000, v191
	v_pk_mul_f32 v[146:147], v[146:147], v[154:155]
	v_pk_mul_f32 v[148:149], v[148:149], v[156:157]
	v_pk_mul_f32 v[150:151], v[150:151], v[158:159]
	v_pk_mul_f32 v[152:153], v[152:153], v[160:161]
	v_pk_mul_f32 v[52:53], v[52:53], v[146:147]
	v_pk_mul_f32 v[54:55], v[54:55], v[148:149]
	v_pk_mul_f32 v[48:49], v[48:49], v[150:151]
	v_pk_mul_f32 v[50:51], v[50:51], v[152:153]
	s_waitcnt vmcnt(8)
	v_lshlrev_b32_e32 v146, 16, v192
	v_and_b32_e32 v147, 0xffff0000, v192
	v_lshlrev_b32_e32 v148, 16, v193
	v_and_b32_e32 v149, 0xffff0000, v193
	v_lshlrev_b32_e32 v150, 16, v194
	v_and_b32_e32 v151, 0xffff0000, v194
	v_lshlrev_b32_e32 v152, 16, v195
	v_and_b32_e32 v153, 0xffff0000, v195
	v_rcp_f32_e32 v146, v146
	v_rcp_f32_e32 v147, v147
	v_rcp_f32_e32 v148, v148
	v_rcp_f32_e32 v149, v149
	v_rcp_f32_e32 v150, v150
	v_rcp_f32_e32 v151, v151
	v_rcp_f32_e32 v152, v152
	v_rcp_f32_e32 v153, v153
	v_lshlrev_b32_e32 v154, 16, v196
	v_and_b32_e32 v155, 0xffff0000, v196
	v_lshlrev_b32_e32 v156, 16, v197
	v_and_b32_e32 v157, 0xffff0000, v197
	v_lshlrev_b32_e32 v158, 16, v198
	v_and_b32_e32 v159, 0xffff0000, v198
	v_lshlrev_b32_e32 v160, 16, v199
	v_and_b32_e32 v161, 0xffff0000, v199
	v_pk_mul_f32 v[146:147], v[146:147], v[154:155]
	v_pk_mul_f32 v[148:149], v[148:149], v[156:157]
	v_pk_mul_f32 v[150:151], v[150:151], v[158:159]
	v_pk_mul_f32 v[152:153], v[152:153], v[160:161]
	v_pk_mul_f32 v[20:21], v[20:21], v[146:147]
	v_pk_mul_f32 v[22:23], v[22:23], v[148:149]
	v_pk_mul_f32 v[16:17], v[16:17], v[150:151]
	v_pk_mul_f32 v[18:19], v[18:19], v[152:153]
	s_waitcnt vmcnt(6)
	v_lshlrev_b32_e32 v146, 16, v200
	v_and_b32_e32 v147, 0xffff0000, v200
	v_lshlrev_b32_e32 v148, 16, v201
	v_and_b32_e32 v149, 0xffff0000, v201
	v_lshlrev_b32_e32 v150, 16, v202
	v_and_b32_e32 v151, 0xffff0000, v202
	v_lshlrev_b32_e32 v152, 16, v203
	v_and_b32_e32 v153, 0xffff0000, v203
	v_rcp_f32_e32 v146, v146
	v_rcp_f32_e32 v147, v147
	v_rcp_f32_e32 v148, v148
	v_rcp_f32_e32 v149, v149
	v_rcp_f32_e32 v150, v150
	v_rcp_f32_e32 v151, v151
	v_rcp_f32_e32 v152, v152
	v_rcp_f32_e32 v153, v153
	v_lshlrev_b32_e32 v154, 16, v204
	v_and_b32_e32 v155, 0xffff0000, v204
	v_lshlrev_b32_e32 v156, 16, v205
	v_and_b32_e32 v157, 0xffff0000, v205
	v_lshlrev_b32_e32 v158, 16, v206
	v_and_b32_e32 v159, 0xffff0000, v206
	v_lshlrev_b32_e32 v160, 16, v207
	v_and_b32_e32 v161, 0xffff0000, v207
	v_pk_mul_f32 v[146:147], v[146:147], v[154:155]
	v_pk_mul_f32 v[148:149], v[148:149], v[156:157]
	v_pk_mul_f32 v[150:151], v[150:151], v[158:159]
	v_pk_mul_f32 v[152:153], v[152:153], v[160:161]
	v_pk_mul_f32 v[44:45], v[44:45], v[146:147]
	v_pk_mul_f32 v[46:47], v[46:47], v[148:149]
	v_pk_mul_f32 v[40:41], v[40:41], v[150:151]
	v_pk_mul_f32 v[42:43], v[42:43], v[152:153]
	s_waitcnt vmcnt(4)
	v_lshlrev_b32_e32 v146, 16, v208
	v_and_b32_e32 v147, 0xffff0000, v208
	v_lshlrev_b32_e32 v148, 16, v209
	v_and_b32_e32 v149, 0xffff0000, v209
	v_lshlrev_b32_e32 v150, 16, v210
	v_and_b32_e32 v151, 0xffff0000, v210
	v_lshlrev_b32_e32 v152, 16, v211
	v_and_b32_e32 v153, 0xffff0000, v211
	v_rcp_f32_e32 v146, v146
	v_rcp_f32_e32 v147, v147
	v_rcp_f32_e32 v148, v148
	v_rcp_f32_e32 v149, v149
	v_rcp_f32_e32 v150, v150
	v_rcp_f32_e32 v151, v151
	v_rcp_f32_e32 v152, v152
	v_rcp_f32_e32 v153, v153
	v_lshlrev_b32_e32 v154, 16, v212
	v_and_b32_e32 v155, 0xffff0000, v212
	v_lshlrev_b32_e32 v156, 16, v213
	v_and_b32_e32 v157, 0xffff0000, v213
	v_lshlrev_b32_e32 v158, 16, v214
	v_and_b32_e32 v159, 0xffff0000, v214
	v_lshlrev_b32_e32 v160, 16, v215
	v_and_b32_e32 v161, 0xffff0000, v215
	v_pk_mul_f32 v[146:147], v[146:147], v[154:155]
	v_pk_mul_f32 v[148:149], v[148:149], v[156:157]
	v_pk_mul_f32 v[150:151], v[150:151], v[158:159]
	v_pk_mul_f32 v[152:153], v[152:153], v[160:161]
	v_pk_mul_f32 v[12:13], v[12:13], v[146:147]
	v_pk_mul_f32 v[14:15], v[14:15], v[148:149]
	v_pk_mul_f32 v[8:9], v[8:9], v[150:151]
	v_pk_mul_f32 v[10:11], v[10:11], v[152:153]
	s_waitcnt vmcnt(2)
	v_lshlrev_b32_e32 v146, 16, v216
	v_and_b32_e32 v147, 0xffff0000, v216
	v_lshlrev_b32_e32 v148, 16, v217
	v_and_b32_e32 v149, 0xffff0000, v217
	v_lshlrev_b32_e32 v150, 16, v218
	v_and_b32_e32 v151, 0xffff0000, v218
	v_lshlrev_b32_e32 v152, 16, v219
	v_and_b32_e32 v153, 0xffff0000, v219
	v_rcp_f32_e32 v146, v146
	v_rcp_f32_e32 v147, v147
	v_rcp_f32_e32 v148, v148
	v_rcp_f32_e32 v149, v149
	v_rcp_f32_e32 v150, v150
	v_rcp_f32_e32 v151, v151
	v_rcp_f32_e32 v152, v152
	v_rcp_f32_e32 v153, v153
	v_lshlrev_b32_e32 v154, 16, v220
	v_and_b32_e32 v155, 0xffff0000, v220
	v_lshlrev_b32_e32 v156, 16, v221
	v_and_b32_e32 v157, 0xffff0000, v221
	v_lshlrev_b32_e32 v158, 16, v222
	v_and_b32_e32 v159, 0xffff0000, v222
	v_lshlrev_b32_e32 v160, 16, v223
	v_and_b32_e32 v161, 0xffff0000, v223
	v_pk_mul_f32 v[146:147], v[146:147], v[154:155]
	v_pk_mul_f32 v[148:149], v[148:149], v[156:157]
	v_pk_mul_f32 v[150:151], v[150:151], v[158:159]
	v_pk_mul_f32 v[152:153], v[152:153], v[160:161]
	v_pk_mul_f32 v[36:37], v[36:37], v[146:147]
	v_pk_mul_f32 v[38:39], v[38:39], v[148:149]
	v_pk_mul_f32 v[32:33], v[32:33], v[150:151]
	v_pk_mul_f32 v[34:35], v[34:35], v[152:153]
	s_waitcnt vmcnt(0)
	v_lshlrev_b32_e32 v146, 16, v224
	v_and_b32_e32 v147, 0xffff0000, v224
	v_lshlrev_b32_e32 v148, 16, v225
	v_and_b32_e32 v149, 0xffff0000, v225
	v_lshlrev_b32_e32 v150, 16, v226
	v_and_b32_e32 v151, 0xffff0000, v226
	v_lshlrev_b32_e32 v152, 16, v227
	v_and_b32_e32 v153, 0xffff0000, v227
	v_rcp_f32_e32 v146, v146
	v_rcp_f32_e32 v147, v147
	v_rcp_f32_e32 v148, v148
	v_rcp_f32_e32 v149, v149
	v_rcp_f32_e32 v150, v150
	v_rcp_f32_e32 v151, v151
	v_rcp_f32_e32 v152, v152
	v_rcp_f32_e32 v153, v153
	v_lshlrev_b32_e32 v154, 16, v228
	v_and_b32_e32 v155, 0xffff0000, v228
	v_lshlrev_b32_e32 v156, 16, v229
	v_and_b32_e32 v157, 0xffff0000, v229
	v_lshlrev_b32_e32 v158, 16, v230
	v_and_b32_e32 v159, 0xffff0000, v230
	v_lshlrev_b32_e32 v160, 16, v231
	v_and_b32_e32 v161, 0xffff0000, v231
	v_pk_mul_f32 v[146:147], v[146:147], v[154:155]
	v_pk_mul_f32 v[148:149], v[148:149], v[156:157]
	v_pk_mul_f32 v[150:151], v[150:151], v[158:159]
	v_pk_mul_f32 v[152:153], v[152:153], v[160:161]
	v_pk_mul_f32 v[4:5], v[4:5], v[146:147]
	v_pk_mul_f32 v[6:7], v[6:7], v[148:149]
	v_pk_mul_f32 v[0:1], v[0:1], v[150:151]
	v_pk_mul_f32 v[2:3], v[2:3], v[152:153]
	s_branch .Lp3e_done
.Lp3e_half1:
	global_load_dwordx4 v[166:169], v142, s[76:77]
	global_load_dwordx4 v[170:173], v142, s[88:89]
	v_add_u32_e32 v145, 0xc000, v142
	global_load_dwordx4 v[174:177], v145, s[76:77]
	global_load_dwordx4 v[178:181], v145, s[88:89]
	v_add_u32_e32 v144, 0x18000, v142
	global_load_dwordx4 v[184:187], v144, s[76:77]
	global_load_dwordx4 v[188:191], v144, s[88:89]
	v_add_u32_e32 v145, 0x24000, v142
	global_load_dwordx4 v[192:195], v145, s[76:77]
	global_load_dwordx4 v[196:199], v145, s[88:89]
	v_add_u32_e32 v144, 0x30000, v142
	global_load_dwordx4 v[200:203], v144, s[76:77]
	global_load_dwordx4 v[204:207], v144, s[88:89]
	v_add_u32_e32 v145, 0x3c000, v142
	global_load_dwordx4 v[208:211], v145, s[76:77]
	global_load_dwordx4 v[212:215], v145, s[88:89]
	v_add_u32_e32 v144, 0x48000, v142
	global_load_dwordx4 v[216:219], v144, s[76:77]
	global_load_dwordx4 v[220:223], v144, s[88:89]
	v_add_u32_e32 v145, 0x54000, v142
	global_load_dwordx4 v[224:227], v145, s[76:77]
	global_load_dwordx4 v[228:231], v145, s[88:89]
	s_waitcnt vmcnt(15)
	v_lshlrev_b32_e32 v146, 16, v166
	v_and_b32_e32 v147, 0xffff0000, v166
	v_lshlrev_b32_e32 v148, 16, v167
	v_and_b32_e32 v149, 0xffff0000, v167
	v_lshlrev_b32_e32 v150, 16, v168
	v_and_b32_e32 v151, 0xffff0000, v168
	v_lshlrev_b32_e32 v152, 16, v169
	v_and_b32_e32 v153, 0xffff0000, v169
	v_pk_mul_f32 v[154:155], v[124:125], v[146:147]
	v_pk_mul_f32 v[156:157], v[126:127], v[148:149]
	v_pk_mul_f32 v[158:159], v[120:121], v[150:151]
	v_pk_mul_f32 v[160:161], v[122:123], v[152:153]
	v_cvt_pk_bf16_f32 v166, v154, v155
	v_cvt_pk_bf16_f32 v167, v156, v157
	v_cvt_pk_bf16_f32 v168, v158, v159
	v_cvt_pk_bf16_f32 v169, v160, v161
	global_store_dwordx4 v143, v[166:169], s[72:73]
	s_waitcnt vmcnt(15)
	v_lshlrev_b32_e32 v146, 16, v170
	v_and_b32_e32 v147, 0xffff0000, v170
	v_lshlrev_b32_e32 v148, 16, v171
	v_and_b32_e32 v149, 0xffff0000, v171
	v_lshlrev_b32_e32 v150, 16, v172
	v_and_b32_e32 v151, 0xffff0000, v172
	v_lshlrev_b32_e32 v152, 16, v173
	v_and_b32_e32 v153, 0xffff0000, v173
	v_pk_mul_f32 v[154:155], v[92:93], v[146:147]
	v_pk_mul_f32 v[156:157], v[94:95], v[148:149]
	v_pk_mul_f32 v[158:159], v[88:89], v[150:151]
	v_pk_mul_f32 v[160:161], v[90:91], v[152:153]
	v_cvt_pk_bf16_f32 v170, v154, v155
	v_cvt_pk_bf16_f32 v171, v156, v157
	v_cvt_pk_bf16_f32 v172, v158, v159
	v_cvt_pk_bf16_f32 v173, v160, v161
	global_store_dwordx4 v143, v[170:173], s[72:73] offset:256
	s_waitcnt vmcnt(15)
	v_lshlrev_b32_e32 v146, 16, v174
	v_and_b32_e32 v147, 0xffff0000, v174
	v_lshlrev_b32_e32 v148, 16, v175
	v_and_b32_e32 v149, 0xffff0000, v175
	v_lshlrev_b32_e32 v150, 16, v176
	v_and_b32_e32 v151, 0xffff0000, v176
	v_lshlrev_b32_e32 v152, 16, v177
	v_and_b32_e32 v153, 0xffff0000, v177
	v_pk_mul_f32 v[154:155], v[116:117], v[146:147]
	v_pk_mul_f32 v[156:157], v[118:119], v[148:149]
	v_pk_mul_f32 v[158:159], v[112:113], v[150:151]
	v_pk_mul_f32 v[160:161], v[114:115], v[152:153]
	v_add_u32_e32 v145, 0x20000, v143
	v_cvt_pk_bf16_f32 v174, v154, v155
	v_cvt_pk_bf16_f32 v175, v156, v157
	v_cvt_pk_bf16_f32 v176, v158, v159
	v_cvt_pk_bf16_f32 v177, v160, v161
	global_store_dwordx4 v145, v[174:177], s[72:73]
	s_waitcnt vmcnt(15)
	v_lshlrev_b32_e32 v146, 16, v178
	v_and_b32_e32 v147, 0xffff0000, v178
	v_lshlrev_b32_e32 v148, 16, v179
	v_and_b32_e32 v149, 0xffff0000, v179
	v_lshlrev_b32_e32 v150, 16, v180
	v_and_b32_e32 v151, 0xffff0000, v180
	v_lshlrev_b32_e32 v152, 16, v181
	v_and_b32_e32 v153, 0xffff0000, v181
	v_pk_mul_f32 v[154:155], v[84:85], v[146:147]
	v_pk_mul_f32 v[156:157], v[86:87], v[148:149]
	v_pk_mul_f32 v[158:159], v[80:81], v[150:151]
	v_pk_mul_f32 v[160:161], v[82:83], v[152:153]
	v_cvt_pk_bf16_f32 v178, v154, v155
	v_cvt_pk_bf16_f32 v179, v156, v157
	v_cvt_pk_bf16_f32 v180, v158, v159
	v_cvt_pk_bf16_f32 v181, v160, v161
	global_store_dwordx4 v145, v[178:181], s[72:73] offset:256
	s_waitcnt vmcnt(15)
	v_lshlrev_b32_e32 v146, 16, v184
	v_and_b32_e32 v147, 0xffff0000, v184
	v_lshlrev_b32_e32 v148, 16, v185
	v_and_b32_e32 v149, 0xffff0000, v185
	v_lshlrev_b32_e32 v150, 16, v186
	v_and_b32_e32 v151, 0xffff0000, v186
	v_lshlrev_b32_e32 v152, 16, v187
	v_and_b32_e32 v153, 0xffff0000, v187
	v_pk_mul_f32 v[154:155], v[108:109], v[146:147]
	v_pk_mul_f32 v[156:157], v[110:111], v[148:149]
	v_pk_mul_f32 v[158:159], v[104:105], v[150:151]
	v_pk_mul_f32 v[160:161], v[106:107], v[152:153]
	v_add_u32_e32 v144, 0x40000, v143
	v_cvt_pk_bf16_f32 v184, v154, v155
	v_cvt_pk_bf16_f32 v185, v156, v157
	v_cvt_pk_bf16_f32 v186, v158, v159
	v_cvt_pk_bf16_f32 v187, v160, v161
	global_store_dwordx4 v144, v[184:187], s[72:73]
	s_waitcnt vmcnt(15)
	v_lshlrev_b32_e32 v146, 16, v188
	v_and_b32_e32 v147, 0xffff0000, v188
	v_lshlrev_b32_e32 v148, 16, v189
	v_and_b32_e32 v149, 0xffff0000, v189
	v_lshlrev_b32_e32 v150, 16, v190
	v_and_b32_e32 v151, 0xffff0000, v190
	v_lshlrev_b32_e32 v152, 16, v191
	v_and_b32_e32 v153, 0xffff0000, v191
	v_pk_mul_f32 v[154:155], v[76:77], v[146:147]
	v_pk_mul_f32 v[156:157], v[78:79], v[148:149]
	v_pk_mul_f32 v[158:159], v[72:73], v[150:151]
	v_pk_mul_f32 v[160:161], v[74:75], v[152:153]
	v_cvt_pk_bf16_f32 v188, v154, v155
	v_cvt_pk_bf16_f32 v189, v156, v157
	v_cvt_pk_bf16_f32 v190, v158, v159
	v_cvt_pk_bf16_f32 v191, v160, v161
	global_store_dwordx4 v144, v[188:191], s[72:73] offset:256
	s_waitcnt vmcnt(15)
	v_lshlrev_b32_e32 v146, 16, v192
	v_and_b32_e32 v147, 0xffff0000, v192
	v_lshlrev_b32_e32 v148, 16, v193
	v_and_b32_e32 v149, 0xffff0000, v193
	v_lshlrev_b32_e32 v150, 16, v194
	v_and_b32_e32 v151, 0xffff0000, v194
	v_lshlrev_b32_e32 v152, 16, v195
	v_and_b32_e32 v153, 0xffff0000, v195
	v_pk_mul_f32 v[154:155], v[100:101], v[146:147]
	v_pk_mul_f32 v[156:157], v[102:103], v[148:149]
	v_pk_mul_f32 v[158:159], v[96:97], v[150:151]
	v_pk_mul_f32 v[160:161], v[98:99], v[152:153]
	v_add_u32_e32 v145, 0x60000, v143
	v_cvt_pk_bf16_f32 v192, v154, v155
	v_cvt_pk_bf16_f32 v193, v156, v157
	v_cvt_pk_bf16_f32 v194, v158, v159
	v_cvt_pk_bf16_f32 v195, v160, v161
	global_store_dwordx4 v145, v[192:195], s[72:73]
	s_waitcnt vmcnt(15)
	v_lshlrev_b32_e32 v146, 16, v196
	v_and_b32_e32 v147, 0xffff0000, v196
	v_lshlrev_b32_e32 v148, 16, v197
	v_and_b32_e32 v149, 0xffff0000, v197
	v_lshlrev_b32_e32 v150, 16, v198
	v_and_b32_e32 v151, 0xffff0000, v198
	v_lshlrev_b32_e32 v152, 16, v199
	v_and_b32_e32 v153, 0xffff0000, v199
	v_pk_mul_f32 v[154:155], v[68:69], v[146:147]
	v_pk_mul_f32 v[156:157], v[70:71], v[148:149]
	v_pk_mul_f32 v[158:159], v[64:65], v[150:151]
	v_pk_mul_f32 v[160:161], v[66:67], v[152:153]
	v_cvt_pk_bf16_f32 v196, v154, v155
	v_cvt_pk_bf16_f32 v197, v156, v157
	v_cvt_pk_bf16_f32 v198, v158, v159
	v_cvt_pk_bf16_f32 v199, v160, v161
	global_store_dwordx4 v145, v[196:199], s[72:73] offset:256
	s_waitcnt vmcnt(15)
	v_lshlrev_b32_e32 v146, 16, v200
	v_and_b32_e32 v147, 0xffff0000, v200
	v_lshlrev_b32_e32 v148, 16, v201
	v_and_b32_e32 v149, 0xffff0000, v201
	v_lshlrev_b32_e32 v150, 16, v202
	v_and_b32_e32 v151, 0xffff0000, v202
	v_lshlrev_b32_e32 v152, 16, v203
	v_and_b32_e32 v153, 0xffff0000, v203
	v_pk_mul_f32 v[154:155], v[60:61], v[146:147]
	v_pk_mul_f32 v[156:157], v[62:63], v[148:149]
	v_pk_mul_f32 v[158:159], v[56:57], v[150:151]
	v_pk_mul_f32 v[160:161], v[58:59], v[152:153]
	v_add_u32_e32 v144, 0x100000, v143
	v_cvt_pk_bf16_f32 v200, v154, v155
	v_cvt_pk_bf16_f32 v201, v156, v157
	v_cvt_pk_bf16_f32 v202, v158, v159
	v_cvt_pk_bf16_f32 v203, v160, v161
	global_store_dwordx4 v144, v[200:203], s[72:73]
	s_waitcnt vmcnt(15)
	v_lshlrev_b32_e32 v146, 16, v204
	v_and_b32_e32 v147, 0xffff0000, v204
	v_lshlrev_b32_e32 v148, 16, v205
	v_and_b32_e32 v149, 0xffff0000, v205
	v_lshlrev_b32_e32 v150, 16, v206
	v_and_b32_e32 v151, 0xffff0000, v206
	v_lshlrev_b32_e32 v152, 16, v207
	v_and_b32_e32 v153, 0xffff0000, v207
	v_pk_mul_f32 v[154:155], v[28:29], v[146:147]
	v_pk_mul_f32 v[156:157], v[30:31], v[148:149]
	v_pk_mul_f32 v[158:159], v[24:25], v[150:151]
	v_pk_mul_f32 v[160:161], v[26:27], v[152:153]
	v_cvt_pk_bf16_f32 v204, v154, v155
	v_cvt_pk_bf16_f32 v205, v156, v157
	v_cvt_pk_bf16_f32 v206, v158, v159
	v_cvt_pk_bf16_f32 v207, v160, v161
	global_store_dwordx4 v144, v[204:207], s[72:73] offset:256
	s_waitcnt vmcnt(15)
	v_lshlrev_b32_e32 v146, 16, v208
	v_and_b32_e32 v147, 0xffff0000, v208
	v_lshlrev_b32_e32 v148, 16, v209
	v_and_b32_e32 v149, 0xffff0000, v209
	v_lshlrev_b32_e32 v150, 16, v210
	v_and_b32_e32 v151, 0xffff0000, v210
	v_lshlrev_b32_e32 v152, 16, v211
	v_and_b32_e32 v153, 0xffff0000, v211
	v_pk_mul_f32 v[154:155], v[52:53], v[146:147]
	v_pk_mul_f32 v[156:157], v[54:55], v[148:149]
	v_pk_mul_f32 v[158:159], v[48:49], v[150:151]
	v_pk_mul_f32 v[160:161], v[50:51], v[152:153]
	v_add_u32_e32 v145, 0x120000, v143
	v_cvt_pk_bf16_f32 v208, v154, v155
	v_cvt_pk_bf16_f32 v209, v156, v157
	v_cvt_pk_bf16_f32 v210, v158, v159
	v_cvt_pk_bf16_f32 v211, v160, v161
	global_store_dwordx4 v145, v[208:211], s[72:73]
	s_waitcnt vmcnt(15)
	v_lshlrev_b32_e32 v146, 16, v212
	v_and_b32_e32 v147, 0xffff0000, v212
	v_lshlrev_b32_e32 v148, 16, v213
	v_and_b32_e32 v149, 0xffff0000, v213
	v_lshlrev_b32_e32 v150, 16, v214
	v_and_b32_e32 v151, 0xffff0000, v214
	v_lshlrev_b32_e32 v152, 16, v215
	v_and_b32_e32 v153, 0xffff0000, v215
	v_pk_mul_f32 v[154:155], v[20:21], v[146:147]
	v_pk_mul_f32 v[156:157], v[22:23], v[148:149]
	v_pk_mul_f32 v[158:159], v[16:17], v[150:151]
	v_pk_mul_f32 v[160:161], v[18:19], v[152:153]
	v_cvt_pk_bf16_f32 v212, v154, v155
	v_cvt_pk_bf16_f32 v213, v156, v157
	v_cvt_pk_bf16_f32 v214, v158, v159
	v_cvt_pk_bf16_f32 v215, v160, v161
	global_store_dwordx4 v145, v[212:215], s[72:73] offset:256
	s_waitcnt vmcnt(15)
	v_lshlrev_b32_e32 v146, 16, v216
	v_and_b32_e32 v147, 0xffff0000, v216
	v_lshlrev_b32_e32 v148, 16, v217
	v_and_b32_e32 v149, 0xffff0000, v217
	v_lshlrev_b32_e32 v150, 16, v218
	v_and_b32_e32 v151, 0xffff0000, v218
	v_lshlrev_b32_e32 v152, 16, v219
	v_and_b32_e32 v153, 0xffff0000, v219
	v_pk_mul_f32 v[154:155], v[44:45], v[146:147]
	v_pk_mul_f32 v[156:157], v[46:47], v[148:149]
	v_pk_mul_f32 v[158:159], v[40:41], v[150:151]
	v_pk_mul_f32 v[160:161], v[42:43], v[152:153]
	v_add_u32_e32 v144, 0x140000, v143
	v_cvt_pk_bf16_f32 v216, v154, v155
	v_cvt_pk_bf16_f32 v217, v156, v157
	v_cvt_pk_bf16_f32 v218, v158, v159
	v_cvt_pk_bf16_f32 v219, v160, v161
	global_store_dwordx4 v144, v[216:219], s[72:73]
	s_waitcnt vmcnt(15)
	v_lshlrev_b32_e32 v146, 16, v220
	v_and_b32_e32 v147, 0xffff0000, v220
	v_lshlrev_b32_e32 v148, 16, v221
	v_and_b32_e32 v149, 0xffff0000, v221
	v_lshlrev_b32_e32 v150, 16, v222
	v_and_b32_e32 v151, 0xffff0000, v222
	v_lshlrev_b32_e32 v152, 16, v223
	v_and_b32_e32 v153, 0xffff0000, v223
	v_pk_mul_f32 v[154:155], v[12:13], v[146:147]
	v_pk_mul_f32 v[156:157], v[14:15], v[148:149]
	v_pk_mul_f32 v[158:159], v[8:9], v[150:151]
	v_pk_mul_f32 v[160:161], v[10:11], v[152:153]
	v_cvt_pk_bf16_f32 v220, v154, v155
	v_cvt_pk_bf16_f32 v221, v156, v157
	v_cvt_pk_bf16_f32 v222, v158, v159
	v_cvt_pk_bf16_f32 v223, v160, v161
	global_store_dwordx4 v144, v[220:223], s[72:73] offset:256
	s_waitcnt vmcnt(15)
	v_lshlrev_b32_e32 v146, 16, v224
	v_and_b32_e32 v147, 0xffff0000, v224
	v_lshlrev_b32_e32 v148, 16, v225
	v_and_b32_e32 v149, 0xffff0000, v225
	v_lshlrev_b32_e32 v150, 16, v226
	v_and_b32_e32 v151, 0xffff0000, v226
	v_lshlrev_b32_e32 v152, 16, v227
	v_and_b32_e32 v153, 0xffff0000, v227
	v_pk_mul_f32 v[154:155], v[36:37], v[146:147]
	v_pk_mul_f32 v[156:157], v[38:39], v[148:149]
	v_pk_mul_f32 v[158:159], v[32:33], v[150:151]
	v_pk_mul_f32 v[160:161], v[34:35], v[152:153]
	v_add_u32_e32 v145, 0x160000, v143
	v_cvt_pk_bf16_f32 v224, v154, v155
	v_cvt_pk_bf16_f32 v225, v156, v157
	v_cvt_pk_bf16_f32 v226, v158, v159
	v_cvt_pk_bf16_f32 v227, v160, v161
	global_store_dwordx4 v145, v[224:227], s[72:73]
	s_waitcnt vmcnt(15)
	v_lshlrev_b32_e32 v146, 16, v228
	v_and_b32_e32 v147, 0xffff0000, v228
	v_lshlrev_b32_e32 v148, 16, v229
	v_and_b32_e32 v149, 0xffff0000, v229
	v_lshlrev_b32_e32 v150, 16, v230
	v_and_b32_e32 v151, 0xffff0000, v230
	v_lshlrev_b32_e32 v152, 16, v231
	v_and_b32_e32 v153, 0xffff0000, v231
	v_pk_mul_f32 v[154:155], v[4:5], v[146:147]
	v_pk_mul_f32 v[156:157], v[6:7], v[148:149]
	v_pk_mul_f32 v[158:159], v[0:1], v[150:151]
	v_pk_mul_f32 v[160:161], v[2:3], v[152:153]
	v_cvt_pk_bf16_f32 v228, v154, v155
	v_cvt_pk_bf16_f32 v229, v156, v157
	v_cvt_pk_bf16_f32 v230, v158, v159
	v_cvt_pk_bf16_f32 v231, v160, v161
	global_store_dwordx4 v145, v[228:231], s[72:73] offset:256
